# LN2 phase: gain/bias vectors loaded once per phase into registers (were reloaded per row behind vmcnt(0), which also drained the next pair prefetch); stacked on +4 epilogue and mseq waits
# speedup vs baseline: 1.0067x; 1.0057x over previous
; __device__ __forceinline__ void row_ln(f32x4 (&v)[4], const float* g, const float* b, int lane) {
;     ...
;     for (int j = 0; j < 4; ++j) { const f32x4 gg = *(const f32x4*)(g + RCOL(lane, j)), bb = *(const f32x4*)(b + RCOL(lane, j)); v[j] = v[j] * rstd * gg + bb; }
; __device__ __forceinline__ void ln2_phase(CArgs& A, Frame& F, int L) {
;     const float* g = A.in[17] + ((size_t)L * 3 + 1) * D; const float* bb = A.in[18] + ((size_t)L * 3 + 1) * D;
;     bf16* X = WSP(bf16, WS_X); const bf16* YS = WSP(bf16, WS_YS); const int* slot = WSP(int, WS_SLOT); const float* gate = WSP(float, WS_GATE);
;     int m0, m1; row_range(F, m0, m1);
;     for (int c0 = m0; c0 < m1; c0 += 32) { const int c1 = (c0 + 32 < m1) ? c0 + 32 : m1;
;         int slv = 0; float gtv = 0.f;
;         if (F.lane < 2 * (c1 - c0)) { slv = slot[2 * c0 + F.lane]; gtv = gate[2 * c0 + F.lane]; }
;         u32x4 nx[2][3][2];
;     ...
;         LN2_LOAD(c0);
.LBB0_1483:
	s_andn2_b64 vcc, exec, s[0:1]
	s_cbranch_vccnz .LBB0_1539
	v_readlane_b32 s2, v253, 5
	v_readlane_b32 s4, v254, 41
	v_readlane_b32 s3, v253, 6
	s_mov_b32 s0, s9
	v_readlane_b32 s1, v253, 11
	v_mbcnt_lo_u32_b32 v0, -1, s0
	v_mbcnt_hi_u32_b32 v3, -1, v0
	v_readlane_b32 s0, v253, 0
	s_lshl_b32 s0, s0, 3
	s_add_i32 s5, s0, s1
	v_readlane_b32 s7, v253, 51
	v_readlane_b32 s8, v253, 52
	s_min_i32 s1, s5, s7
	s_mul_i32 s6, s8, s5
	s_add_i32 s0, s6, s1
	s_cmp_lt_i32 s5, s7
	s_cselect_b64 s[10:11], -1, 0
	s_cmp_lg_u64 s[10:11], 0
	s_addc_u32 s8, s0, s8
	s_cmp_ge_i32 s0, s8
	s_cbranch_scc1 .LBB0_1493
	s_load_dwordx2 s[10:11], s[2:3], 0xe8
	s_load_dwordx4 s[12:15], s[2:3], 0x88
	s_mul_hi_i32 s7, s4, 0x3000
	s_mul_i32 s16, s4, 0x3000
	v_lshlrev_b32_e32 v4, 3, v3
	s_waitcnt lgkmcnt(0)
	s_add_u32 s2, s10, 0x3ff06000
	s_addc_u32 s3, s11, 0
	s_add_u32 s4, s10, 0x3fee5000
	s_addc_u32 s5, s11, 0
	s_add_u32 s16, s16, 0x1000
	s_addc_u32 s7, s7, 0
	s_add_u32 s14, s14, s16
	s_addc_u32 s15, s15, s7
	v_ashrrev_i32_e32 v5, 31, v4
	s_add_u32 s12, s12, s16
	v_lshl_add_u64 v[6:7], v[4:5], 1, s[10:11]
	s_mov_b64 s[10:11], 0x31584000
	s_addc_u32 s13, s13, s7
	v_lshl_add_u64 v[0:1], v[6:7], 0, s[10:11]
	s_mov_b64 s[10:11], 0x7680000
	v_lshlrev_b64 v[4:5], 2, v[4:5]
	s_add_i32 s1, s6, s1
	v_lshl_add_u64 v[100:101], v[6:7], 0, s[10:11]
	v_lshl_add_u64 v[102:103], s[12:13], 0, v[4:5]
	v_lshl_add_u64 v[104:105], s[14:15], 0, v[4:5]
	global_load_dwordx4 v[124:127], v[102:103], off
	global_load_dwordx4 v[128:131], v[102:103], off offset:16
	global_load_dwordx4 v[132:135], v[102:103], off offset:2048
	global_load_dwordx4 v[136:139], v[102:103], off offset:2064
	global_load_dwordx4 v[140:143], v[104:105], off
	global_load_dwordx4 v[144:147], v[104:105], off offset:16
	global_load_dwordx4 v[148:151], v[104:105], off offset:2048
	global_load_dwordx4 v[152:155], v[104:105], off offset:2064
	s_add_i32 s14, s1, 3
	s_add_i32 s6, s1, 2
	s_branch .LBB0_1487

; __device__ __forceinline__ float bflo(unsigned w) { return __uint_as_float(w << 16); }
; __device__ __forceinline__ float bfhi(unsigned w) { return __uint_as_float(w & 0xffff0000u); }
; __device__ __forceinline__ float wave_sum(float v) { return rdlane(dpp_sum63(v), 63); }
; __device__ __forceinline__ void row_ln(f32x4 (&v)[4], const float* g, const float* b, int lane) {
;     float s = 0.f;
; #pragma unroll
;     for (int j = 0; j < 4; ++j) s += (v[j][0] + v[j][1]) + (v[j][2] + v[j][3]);
;     const float mean = wave_sum(s) * (1.f / D); float s2 = 0.f;
; #pragma unroll
;     for (int j = 0; j < 4; ++j) { v[j] = v[j] - mean; s2 += (v[j][0] * v[j][0] + v[j][1] * v[j][1]) + (v[j][2] * v[j][2] + v[j][3] * v[j][3]); }
;     const float rstd = 1.0f / sqrtf(wave_sum(s2) * (1.f / D) + LN_EPS);
; __device__ __forceinline__ void ln2_phase(CArgs& A, Frame& F, int L) {
;     ...
;             for (int r = 0; r < 2; ++r) { const int mm = (m + r < c1) ? m + r : c1 - 1; const int i_ = 2 * (mm - c0);
;                 const float g0 = __builtin_bit_cast(float, __builtin_amdgcn_readlane(__builtin_bit_cast(int, gtv), i_)), g1 = __builtin_bit_cast(float, __builtin_amdgcn_readlane(__builtin_bit_cast(int, gtv), i_ + 1));
;                 f32x4 v[4]; row_unpack(cur[r][0], v);
; #pragma unroll
;                 for (int j2 = 0; j2 < 2; ++j2) { const unsigned a0[4] = {cur[r][1][j2].x, cur[r][1][j2].y, cur[r][1][j2].z, cur[r][1][j2].w}, a1[4] = {cur[r][2][j2].x, cur[r][2][j2].y, cur[r][2][j2].z, cur[r][2][j2].w};
; #pragma unroll
;                     for (int q = 0; q < 4; ++q) { f32x4& vv = v[2 * j2 + (q >> 1)]; const int i0 = 2 * (q & 1);
;                         vv[i0] = vv[i0] * DN_ALPHA + (g0 * bflo(a0[q]) + g1 * bflo(a1[q])); vv[i0 + 1] = vv[i0 + 1] * DN_ALPHA + (g0 * bfhi(a0[q]) + g1 * bfhi(a1[q])); } }
.LBB0_1490:
	s_add_i32 s10, s17, -3
	s_min_i32 s10, s10, s7
	s_sub_i32 s11, s10, s0
	s_lshl_b32 s11, s11, 1
	v_readlane_b32 s13, v109, s11
	s_or_b32 s11, s11, 1
	v_readlane_b32 s12, v109, s11
	v_lshlrev_b32_e32 v116, 16, v92
	v_and_b32_e32 v117, 0xffff0000, v88
	v_lshlrev_b32_e32 v112, 16, v88
	v_and_b32_e32 v113, 0xffff0000, v92
	v_pk_mul_f32 v[116:117], s[12:13], v[116:117] op_sel:[1,0] op_sel_hi:[0,1]
	v_lshlrev_b32_e32 v110, 16, v96
	v_and_b32_e32 v111, 0xffff0000, v96
	v_pk_fma_f32 v[112:113], v[112:113], s[12:13], v[116:117]
	v_lshlrev_b32_e32 v88, 16, v93
	v_pk_fma_f32 v[110:111], v[110:111], s[30:31], v[112:113] op_sel_hi:[1,0,1]
	v_lshlrev_b32_e32 v112, 16, v89
	v_and_b32_e32 v89, 0xffff0000, v89
	v_and_b32_e32 v113, 0xffff0000, v93
	v_pk_mul_f32 v[88:89], s[12:13], v[88:89] op_sel:[1,0] op_sel_hi:[0,1]
	v_lshlrev_b32_e32 v96, 16, v97
	v_and_b32_e32 v97, 0xffff0000, v97
	v_pk_fma_f32 v[88:89], v[112:113], s[12:13], v[88:89]
	v_lshlrev_b32_e32 v112, 16, v94
	v_and_b32_e32 v113, 0xffff0000, v90
	v_pk_fma_f32 v[88:89], v[96:97], s[30:31], v[88:89] op_sel_hi:[1,0,1]
	v_lshlrev_b32_e32 v96, 16, v90
	v_and_b32_e32 v97, 0xffff0000, v94
	v_pk_mul_f32 v[112:113], s[12:13], v[112:113] op_sel:[1,0] op_sel_hi:[0,1]
	v_lshlrev_b32_e32 v92, 16, v98
	v_and_b32_e32 v93, 0xffff0000, v98
	v_pk_fma_f32 v[96:97], v[96:97], s[12:13], v[112:113]
	v_lshlrev_b32_e32 v90, 16, v95
	v_pk_fma_f32 v[112:113], v[92:93], s[30:31], v[96:97] op_sel_hi:[1,0,1]
	v_lshlrev_b32_e32 v96, 16, v91
	v_and_b32_e32 v91, 0xffff0000, v91
	v_and_b32_e32 v97, 0xffff0000, v95
	v_pk_mul_f32 v[90:91], s[12:13], v[90:91] op_sel:[1,0] op_sel_hi:[0,1]
	v_pk_fma_f32 v[90:91], v[96:97], s[12:13], v[90:91]
	v_lshlrev_b32_e32 v96, 16, v80
	v_and_b32_e32 v97, 0xffff0000, v76
	v_lshlrev_b32_e32 v92, 16, v99
	v_and_b32_e32 v93, 0xffff0000, v99
	v_lshlrev_b32_e32 v94, 16, v76
	v_and_b32_e32 v95, 0xffff0000, v80
	v_pk_mul_f32 v[96:97], s[12:13], v[96:97] op_sel:[1,0] op_sel_hi:[0,1]
	v_pk_fma_f32 v[90:91], v[92:93], s[30:31], v[90:91] op_sel_hi:[1,0,1]
	v_lshlrev_b32_e32 v92, 16, v84
	v_and_b32_e32 v93, 0xffff0000, v84
	v_pk_fma_f32 v[94:95], v[94:95], s[12:13], v[96:97]
	v_lshlrev_b32_e32 v76, 16, v81
	v_pk_fma_f32 v[92:93], v[92:93], s[30:31], v[94:95] op_sel_hi:[1,0,1]
	v_lshlrev_b32_e32 v94, 16, v77
	v_and_b32_e32 v77, 0xffff0000, v77
	v_and_b32_e32 v95, 0xffff0000, v81
	v_pk_mul_f32 v[76:77], s[12:13], v[76:77] op_sel:[1,0] op_sel_hi:[0,1]
	v_lshlrev_b32_e32 v84, 16, v85
	v_and_b32_e32 v85, 0xffff0000, v85
	v_pk_fma_f32 v[76:77], v[94:95], s[12:13], v[76:77]
	v_lshlrev_b32_e32 v80, 16, v82
	v_and_b32_e32 v81, 0xffff0000, v78
	v_pk_fma_f32 v[96:97], v[84:85], s[30:31], v[76:77] op_sel_hi:[1,0,1]
	v_lshlrev_b32_e32 v76, 16, v78
	v_and_b32_e32 v77, 0xffff0000, v82
	v_pk_mul_f32 v[80:81], s[12:13], v[80:81] op_sel:[1,0] op_sel_hi:[0,1]
	v_pk_fma_f32 v[76:77], v[76:77], s[12:13], v[80:81]
	v_lshlrev_b32_e32 v80, 16, v79
	v_lshlrev_b32_e32 v78, 16, v83
	v_and_b32_e32 v79, 0xffff0000, v79
	v_lshlrev_b32_e32 v114, 16, v86
	v_and_b32_e32 v115, 0xffff0000, v86
	v_and_b32_e32 v81, 0xffff0000, v83
	v_pk_mul_f32 v[78:79], s[12:13], v[78:79] op_sel:[1,0] op_sel_hi:[0,1]
	v_pk_fma_f32 v[94:95], v[114:115], s[30:31], v[76:77] op_sel_hi:[1,0,1]
	v_lshlrev_b32_e32 v76, 16, v87
	v_and_b32_e32 v77, 0xffff0000, v87
	v_pk_fma_f32 v[78:79], v[80:81], s[12:13], v[78:79]
	v_mov_b32_e32 v80, v113
	v_pk_fma_f32 v[98:99], v[76:77], s[30:31], v[78:79] op_sel_hi:[1,0,1]
	v_mov_b32_e32 v76, v110
	v_mov_b32_e32 v77, v88
	v_mov_b32_e32 v78, v111
	v_mov_b32_e32 v79, v89
	v_pk_add_f32 v[76:77], v[76:77], v[78:79]
	v_mov_b32_e32 v78, v112
	v_mov_b32_e32 v79, v90
	v_mov_b32_e32 v81, v91
	v_pk_add_f32 v[78:79], v[78:79], v[80:81]
	v_add_f32_e32 v76, v76, v77
	v_pk_add_f32 v[78:79], v[78:79], v[78:79] op_sel_hi:[0,1]
	v_pk_add_f32 v[80:81], v[92:93], v[92:93] op_sel_hi:[0,1]
	v_pk_add_f32 v[82:83], v[96:97], v[96:97] op_sel_hi:[0,1]
	v_add_f32_e32 v77, 0, v76
	v_mov_b32_e32 v80, v94
	v_mov_b32_e32 v82, v95
	v_mov_b32_e32 v78, v98
	v_mov_b32_e32 v76, v99
	v_pk_add_f32 v[80:81], v[80:81], v[82:83]
	v_pk_add_f32 v[76:77], v[78:79], v[76:77]
	s_add_i32 s1, s1, 4
	v_pk_add_f32 v[76:77], v[80:81], v[76:77]
	s_nop 0
	v_add_f32_e32 v76, v76, v77
	v_mov_b32_e32 v77, v2
	s_nop 0
	v_add_f32_dpp v76, v76, v76 quad_perm:[1,0,3,2] row_mask:0xf bank_mask:0xf bound_ctrl:1
	s_nop 1
	v_add_f32_dpp v76, v76, v76 quad_perm:[2,3,0,1] row_mask:0xf bank_mask:0xf bound_ctrl:1
	s_nop 1
	v_add_f32_dpp v76, v76, v76 row_half_mirror row_mask:0xf bank_mask:0xf bound_ctrl:1
	s_nop 1
	v_add_f32_dpp v76, v76, v76 row_mirror row_mask:0xf bank_mask:0xf bound_ctrl:1
	s_nop 1
	v_mov_b32_dpp v77, v76 row_bcast:15 row_mask:0xa bank_mask:0xf
	v_add_f32_e32 v76, v76, v77
	v_mov_b32_e32 v77, v2
	s_nop 1
	v_mov_b32_dpp v77, v76 row_bcast:31 row_mask:0xc bank_mask:0xf
	v_add_f32_e32 v76, v76, v77
	s_nop 0
	v_readlane_b32 s11, v76, 63
	s_nop 1
	v_fmac_f32_e32 v89, s11, v236
	v_fmac_f32_e32 v111, s11, v236
	v_fma_f32 v88, s11, v236, v88
	v_fma_f32 v110, s11, v236, v110
	v_mul_f32_e32 v76, v111, v111
	v_mul_f32_e32 v77, v89, v89
	v_fmac_f32_e32 v76, v110, v110
	v_fmac_f32_e32 v77, v88, v88
	v_fmac_f32_e32 v91, s11, v236
	v_fmac_f32_e32 v113, s11, v236
	v_add_f32_e32 v76, v76, v77
	v_fma_f32 v90, s11, v236, v90
	v_fma_f32 v112, s11, v236, v112
	v_mul_f32_e32 v77, v113, v113
	v_mul_f32_e32 v78, v91, v91
	v_fmac_f32_e32 v77, v112, v112
	v_fmac_f32_e32 v78, v90, v90
	v_add_f32_e32 v77, v77, v78
	v_fmac_f32_e32 v97, s11, v236
	v_fmac_f32_e32 v93, s11, v236
	v_add_f32_e32 v76, v76, v77
	v_fma_f32 v96, s11, v236, v96
	v_fma_f32 v92, s11, v236, v92
	v_mul_f32_e32 v77, v93, v93
; __device__ __forceinline__ float wave_sum(float v) { return rdlane(dpp_sum63(v), 63); }
; __device__ __forceinline__ void row_ln(f32x4 (&v)[4], const float* g, const float* b, int lane) {
;     ...
;     const float rstd = 1.0f / sqrtf(wave_sum(s2) * (1.f / D) + LN_EPS);
; #pragma unroll
;     for (int j = 0; j < 4; ++j) { const f32x4 gg = *(const f32x4*)(g + RCOL(lane, j)), bb = *(const f32x4*)(b + RCOL(lane, j)); v[j] = v[j] * rstd * gg + bb; }
; __device__ __forceinline__ void ln2_phase(CArgs& A, Frame& F, int L) {
;     ...
;                 row_ln(v, g, bb, F.lane);
;                 row_store_bf(X + (size_t)mm * D, F.lane, v); }
	v_mul_f32_e32 v78, v97, v97
	v_fmac_f32_e32 v77, v92, v92
	v_fmac_f32_e32 v78, v96, v96
	v_add_f32_e32 v77, v77, v78
	v_fmac_f32_e32 v99, s11, v236
	v_fmac_f32_e32 v95, s11, v236
	v_add_f32_e32 v76, v77, v76
	v_fma_f32 v98, s11, v236, v98
	v_fma_f32 v94, s11, v236, v94
	v_mul_f32_e32 v77, v95, v95
	v_mul_f32_e32 v78, v99, v99
	v_fmac_f32_e32 v77, v94, v94
	v_fmac_f32_e32 v78, v98, v98
	v_add_f32_e32 v77, v77, v78
	v_add_f32_e32 v76, v77, v76
	v_mov_b32_e32 v77, v2
	s_nop 0
	v_add_f32_dpp v76, v76, v76 quad_perm:[1,0,3,2] row_mask:0xf bank_mask:0xf bound_ctrl:1
	s_nop 1
	v_add_f32_dpp v76, v76, v76 quad_perm:[2,3,0,1] row_mask:0xf bank_mask:0xf bound_ctrl:1
	s_nop 1
	v_add_f32_dpp v76, v76, v76 row_half_mirror row_mask:0xf bank_mask:0xf bound_ctrl:1
	s_nop 1
	v_add_f32_dpp v76, v76, v76 row_mirror row_mask:0xf bank_mask:0xf bound_ctrl:1
	s_nop 1
	v_mov_b32_dpp v77, v76 row_bcast:15 row_mask:0xa bank_mask:0xf
	v_add_f32_e32 v76, v76, v77
	v_mov_b32_e32 v77, v2
	s_nop 1
	v_mov_b32_dpp v77, v76 row_bcast:31 row_mask:0xc bank_mask:0xf
	v_add_f32_e32 v76, v76, v77
	s_nop 0
	v_readlane_b32 s11, v76, 63
	s_nop 1
	v_fma_f32 v76, s11, v237, v252
	v_cmp_gt_f32_e32 vcc, s31, v76
	v_mul_f32_e32 v77, 0x4f800000, v76
	s_ashr_i32 s11, s10, 31
	v_cndmask_b32_e32 v76, v76, v77, vcc
	v_sqrt_f32_e32 v77, v76
	s_lshl_b64 s[10:11], s[10:11], 11
	v_add_u32_e32 v78, -1, v77
	v_fma_f32 v79, -v78, v77, v76
	v_cmp_ge_f32_e64 s[38:39], 0, v79
	v_add_u32_e32 v79, 1, v77
	s_nop 0
	v_cndmask_b32_e64 v78, v77, v78, s[38:39]
	v_fma_f32 v77, -v79, v77, v76
	v_cmp_lt_f32_e64 s[38:39], 0, v77
	s_nop 1
	v_cndmask_b32_e64 v77, v78, v79, s[38:39]
	v_mul_f32_e32 v78, 0x37800000, v77
	v_cndmask_b32_e32 v77, v77, v78, vcc
	v_cmp_class_f32_e32 vcc, v76, v234
	s_nop 1
	v_cndmask_b32_e32 v76, v77, v76, vcc
	v_div_scale_f32 v77, s[12:13], v76, v76, 1.0
	v_rcp_f32_e32 v78, v77
	s_nop 0
	v_fma_f32 v79, -v77, v78, 1.0
	v_fmac_f32_e32 v78, v79, v78
	v_div_scale_f32 v79, vcc, 1.0, v76, 1.0
	v_mul_f32_e32 v80, v79, v78
	v_fma_f32 v81, -v77, v80, v79
	v_fmac_f32_e32 v80, v81, v78
	v_fma_f32 v77, -v77, v80, v79
	v_div_fmas_f32 v77, v77, v78, v80
	v_div_fixup_f32 v108, v77, v76, 1.0
	v_mov_b64_e32 v[76:77], v[128:129]
	v_mov_b64_e32 v[78:79], v[130:131]
	v_mov_b64_e32 v[80:81], v[124:125]
	v_mov_b64_e32 v[82:83], v[126:127]
	v_mov_b64_e32 v[84:85], v[144:145]
	v_mov_b64_e32 v[86:87], v[146:147]
	v_mov_b64_e32 v[114:115], v[140:141]
	v_mov_b64_e32 v[116:117], v[142:143]
	v_pk_mul_f32 v[120:121], v[110:111], v[108:109] op_sel_hi:[1,0]
	v_pk_mul_f32 v[88:89], v[88:89], v[108:109] op_sel_hi:[1,0]
	v_pk_mul_f32 v[92:93], v[92:93], v[108:109] op_sel_hi:[1,0]
	v_pk_mul_f32 v[96:97], v[96:97], v[108:109] op_sel_hi:[1,0]
	v_pk_fma_f32 v[110:111], v[82:83], v[88:89], v[116:117]
	v_pk_fma_f32 v[114:115], v[80:81], v[120:121], v[114:115]
	v_pk_mul_f32 v[80:81], v[112:113], v[108:109] op_sel_hi:[1,0]
	v_pk_mul_f32 v[82:83], v[90:91], v[108:109] op_sel_hi:[1,0]
	v_pk_fma_f32 v[116:117], v[76:77], v[80:81], v[84:85]
	v_pk_fma_f32 v[112:113], v[78:79], v[82:83], v[86:87]
	v_mov_b64_e32 v[76:77], v[136:137]
	v_mov_b64_e32 v[78:79], v[138:139]
	v_mov_b64_e32 v[84:85], v[132:133]
	v_mov_b64_e32 v[86:87], v[134:135]
	v_mov_b64_e32 v[80:81], v[152:153]
	v_mov_b64_e32 v[82:83], v[154:155]
	v_mov_b64_e32 v[88:89], v[148:149]
	v_mov_b64_e32 v[90:91], v[150:151]
	v_pk_fma_f32 v[84:85], v[84:85], v[92:93], v[88:89]
	v_pk_mul_f32 v[88:89], v[94:95], v[108:109] op_sel_hi:[1,0]
	v_pk_fma_f32 v[86:87], v[86:87], v[96:97], v[90:91]
	v_pk_fma_f32 v[80:81], v[76:77], v[88:89], v[80:81]
	v_lshl_add_u64 v[88:89], v[100:101], 0, s[10:11]
	s_add_i32 s10, s17, -2
	s_min_i32 s10, s10, s7
	s_sub_i32 s11, s10, s0
	v_pk_mul_f32 v[90:91], v[98:99], v[108:109] op_sel_hi:[1,0]
	s_lshl_b32 s11, s11, 1
	v_pk_fma_f32 v[82:83], v[78:79], v[90:91], v[82:83]
	v_cvt_pk_bf16_f32 v76, v114, v115
	v_cvt_pk_bf16_f32 v77, v110, v111
	v_cvt_pk_bf16_f32 v78, v116, v117
	v_cvt_pk_bf16_f32 v79, v112, v113
	v_readlane_b32 s13, v109, s11
	s_or_b32 s11, s11, 1
	global_store_dwordx4 v[88:89], v[76:79], off
	v_readlane_b32 s12, v109, s11
	s_add_i32 s17, s17, 2
	v_cvt_pk_bf16_f32 v76, v84, v85
	v_cvt_pk_bf16_f32 v77, v86, v87
	v_cvt_pk_bf16_f32 v78, v80, v81
	v_cvt_pk_bf16_f32 v79, v82, v83
	v_lshlrev_b32_e32 v82, 16, v68
	v_and_b32_e32 v83, 0xffff0000, v64
	v_lshlrev_b32_e32 v80, 16, v64
	v_and_b32_e32 v81, 0xffff0000, v68
	v_pk_mul_f32 v[82:83], s[12:13], v[82:83] op_sel:[1,0] op_sel_hi:[0,1]
	global_store_dwordx4 v[88:89], v[76:79], off offset:1024
	v_pk_fma_f32 v[80:81], v[80:81], s[12:13], v[82:83]
	v_lshlrev_b32_e32 v64, 16, v69
	v_lshlrev_b32_e32 v78, 16, v72
	v_and_b32_e32 v79, 0xffff0000, v72
	v_pk_fma_f32 v[78:79], v[78:79], s[30:31], v[80:81] op_sel_hi:[1,0,1]
	v_lshlrev_b32_e32 v80, 16, v65
	v_and_b32_e32 v65, 0xffff0000, v65
	v_and_b32_e32 v81, 0xffff0000, v69
	v_pk_mul_f32 v[64:65], s[12:13], v[64:65] op_sel:[1,0] op_sel_hi:[0,1]
	v_lshlrev_b32_e32 v72, 16, v73
	v_and_b32_e32 v73, 0xffff0000, v73
	v_pk_fma_f32 v[64:65], v[80:81], s[12:13], v[64:65]
	v_lshlrev_b32_e32 v80, 16, v70
	v_and_b32_e32 v81, 0xffff0000, v66
	v_pk_fma_f32 v[64:65], v[72:73], s[30:31], v[64:65] op_sel_hi:[1,0,1]
	v_lshlrev_b32_e32 v72, 16, v66
	v_and_b32_e32 v73, 0xffff0000, v70
	v_pk_mul_f32 v[80:81], s[12:13], v[80:81] op_sel:[1,0] op_sel_hi:[0,1]
	v_lshlrev_b32_e32 v68, 16, v74
	v_and_b32_e32 v69, 0xffff0000, v74
	v_pk_fma_f32 v[72:73], v[72:73], s[12:13], v[80:81]
	v_lshlrev_b32_e32 v66, 16, v71
	v_pk_fma_f32 v[80:81], v[68:69], s[30:31], v[72:73] op_sel_hi:[1,0,1]
	v_lshlrev_b32_e32 v72, 16, v67
	v_and_b32_e32 v67, 0xffff0000, v67
	v_and_b32_e32 v73, 0xffff0000, v71
; __device__ __forceinline__ float bflo(unsigned w) { return __uint_as_float(w << 16); }
; __device__ __forceinline__ float bfhi(unsigned w) { return __uint_as_float(w & 0xffff0000u); }
; __device__ __forceinline__ float wave_sum(float v) { return rdlane(dpp_sum63(v), 63); }
; __device__ __forceinline__ void row_ln(f32x4 (&v)[4], const float* g, const float* b, int lane) {
;     ...
;     for (int j = 0; j < 4; ++j) s += (v[j][0] + v[j][1]) + (v[j][2] + v[j][3]);
;     const float mean = wave_sum(s) * (1.f / D); float s2 = 0.f;
; #pragma unroll
;     for (int j = 0; j < 4; ++j) { v[j] = v[j] - mean; s2 += (v[j][0] * v[j][0] + v[j][1] * v[j][1]) + (v[j][2] * v[j][2] + v[j][3] * v[j][3]); }
;     const float rstd = 1.0f / sqrtf(wave_sum(s2) * (1.f / D) + LN_EPS);
; __device__ __forceinline__ void ln2_phase(CArgs& A, Frame& F, int L) {
;     ...
;             for (int r = 0; r < 2; ++r) { const int mm = (m + r < c1) ? m + r : c1 - 1; const int i_ = 2 * (mm - c0);
;                 const float g0 = __builtin_bit_cast(float, __builtin_amdgcn_readlane(__builtin_bit_cast(int, gtv), i_)), g1 = __builtin_bit_cast(float, __builtin_amdgcn_readlane(__builtin_bit_cast(int, gtv), i_ + 1));
;                 f32x4 v[4]; row_unpack(cur[r][0], v);
; #pragma unroll
;                 for (int j2 = 0; j2 < 2; ++j2) { const unsigned a0[4] = {cur[r][1][j2].x, cur[r][1][j2].y, cur[r][1][j2].z, cur[r][1][j2].w}, a1[4] = {cur[r][2][j2].x, cur[r][2][j2].y, cur[r][2][j2].z, cur[r][2][j2].w};
; #pragma unroll
;                     for (int q = 0; q < 4; ++q) { f32x4& vv = v[2 * j2 + (q >> 1)]; const int i0 = 2 * (q & 1);
;                         vv[i0] = vv[i0] * DN_ALPHA + (g0 * bflo(a0[q]) + g1 * bflo(a1[q])); vv[i0 + 1] = vv[i0 + 1] * DN_ALPHA + (g0 * bfhi(a0[q]) + g1 * bfhi(a1[q])); } }
;                 row_ln(v, g, bb, F.lane);
	v_pk_mul_f32 v[66:67], s[12:13], v[66:67] op_sel:[1,0] op_sel_hi:[0,1]
	v_pk_fma_f32 v[66:67], v[72:73], s[12:13], v[66:67]
	v_lshlrev_b32_e32 v72, 16, v56
	v_and_b32_e32 v73, 0xffff0000, v52
	v_lshlrev_b32_e32 v68, 16, v75
	v_and_b32_e32 v69, 0xffff0000, v75
	v_lshlrev_b32_e32 v70, 16, v52
	v_and_b32_e32 v71, 0xffff0000, v56
	v_pk_mul_f32 v[72:73], s[12:13], v[72:73] op_sel:[1,0] op_sel_hi:[0,1]
	v_pk_fma_f32 v[66:67], v[68:69], s[30:31], v[66:67] op_sel_hi:[1,0,1]
	v_lshlrev_b32_e32 v68, 16, v60
	v_and_b32_e32 v69, 0xffff0000, v60
	v_pk_fma_f32 v[70:71], v[70:71], s[12:13], v[72:73]
	v_lshlrev_b32_e32 v52, 16, v57
	v_pk_fma_f32 v[68:69], v[68:69], s[30:31], v[70:71] op_sel_hi:[1,0,1]
	v_lshlrev_b32_e32 v70, 16, v53
	v_and_b32_e32 v53, 0xffff0000, v53
	v_and_b32_e32 v71, 0xffff0000, v57
	v_pk_mul_f32 v[52:53], s[12:13], v[52:53] op_sel:[1,0] op_sel_hi:[0,1]
	v_lshlrev_b32_e32 v60, 16, v61
	v_and_b32_e32 v61, 0xffff0000, v61
	v_pk_fma_f32 v[52:53], v[70:71], s[12:13], v[52:53]
	v_lshlrev_b32_e32 v56, 16, v58
	v_and_b32_e32 v57, 0xffff0000, v54
	v_pk_fma_f32 v[72:73], v[60:61], s[30:31], v[52:53] op_sel_hi:[1,0,1]
	v_lshlrev_b32_e32 v52, 16, v54
	v_and_b32_e32 v53, 0xffff0000, v58
	v_pk_mul_f32 v[56:57], s[12:13], v[56:57] op_sel:[1,0] op_sel_hi:[0,1]
	v_pk_fma_f32 v[52:53], v[52:53], s[12:13], v[56:57]
	v_lshlrev_b32_e32 v56, 16, v55
	v_lshlrev_b32_e32 v54, 16, v59
	v_and_b32_e32 v55, 0xffff0000, v55
	v_lshlrev_b32_e32 v76, 16, v62
	v_and_b32_e32 v77, 0xffff0000, v62
	v_and_b32_e32 v57, 0xffff0000, v59
	v_pk_mul_f32 v[54:55], s[12:13], v[54:55] op_sel:[1,0] op_sel_hi:[0,1]
	v_pk_fma_f32 v[70:71], v[76:77], s[30:31], v[52:53] op_sel_hi:[1,0,1]
	v_lshlrev_b32_e32 v52, 16, v63
	v_and_b32_e32 v53, 0xffff0000, v63
	v_pk_fma_f32 v[54:55], v[56:57], s[12:13], v[54:55]
	v_mov_b32_e32 v56, v81
	v_pk_fma_f32 v[74:75], v[52:53], s[30:31], v[54:55] op_sel_hi:[1,0,1]
	v_mov_b32_e32 v52, v78
	v_mov_b32_e32 v53, v64
	v_mov_b32_e32 v54, v79
	v_mov_b32_e32 v55, v65
	v_pk_add_f32 v[52:53], v[52:53], v[54:55]
	v_mov_b32_e32 v54, v80
	v_mov_b32_e32 v55, v66
	v_mov_b32_e32 v57, v67
	v_pk_add_f32 v[54:55], v[54:55], v[56:57]
	v_add_f32_e32 v52, v52, v53
	v_pk_add_f32 v[54:55], v[54:55], v[54:55] op_sel_hi:[0,1]
	v_pk_add_f32 v[56:57], v[68:69], v[68:69] op_sel_hi:[0,1]
	v_pk_add_f32 v[58:59], v[72:73], v[72:73] op_sel_hi:[0,1]
	v_add_f32_e32 v53, 0, v52
	v_mov_b32_e32 v56, v70
	v_mov_b32_e32 v58, v71
	v_mov_b32_e32 v54, v74
	v_mov_b32_e32 v52, v75
	v_pk_add_f32 v[56:57], v[56:57], v[58:59]
	v_pk_add_f32 v[52:53], v[54:55], v[52:53]
	s_nop 0
	v_pk_add_f32 v[52:53], v[56:57], v[52:53]
	s_nop 0
	v_add_f32_e32 v52, v52, v53
	v_mov_b32_e32 v53, v2
	s_nop 0
	v_add_f32_dpp v52, v52, v52 quad_perm:[1,0,3,2] row_mask:0xf bank_mask:0xf bound_ctrl:1
	s_nop 0
	s_nop 0
	v_add_f32_dpp v52, v52, v52 quad_perm:[2,3,0,1] row_mask:0xf bank_mask:0xf bound_ctrl:1
	s_nop 0
	s_nop 0
	v_add_f32_dpp v52, v52, v52 row_half_mirror row_mask:0xf bank_mask:0xf bound_ctrl:1
	s_nop 1
	v_add_f32_dpp v52, v52, v52 row_mirror row_mask:0xf bank_mask:0xf bound_ctrl:1
	s_nop 1
	v_mov_b32_dpp v53, v52 row_bcast:15 row_mask:0xa bank_mask:0xf
	v_add_f32_e32 v52, v52, v53
	v_mov_b32_e32 v53, v2
	s_nop 1
	v_mov_b32_dpp v53, v52 row_bcast:31 row_mask:0xc bank_mask:0xf
	v_add_f32_e32 v52, v52, v53
	s_nop 0
	v_readlane_b32 s11, v52, 63
	s_nop 1
	v_fmac_f32_e32 v65, s11, v236
	v_fmac_f32_e32 v79, s11, v236
	v_fma_f32 v64, s11, v236, v64
	v_fma_f32 v78, s11, v236, v78
	v_mul_f32_e32 v52, v79, v79
	v_mul_f32_e32 v53, v65, v65
	v_fmac_f32_e32 v52, v78, v78
	v_fmac_f32_e32 v53, v64, v64
	v_fmac_f32_e32 v67, s11, v236
	v_fmac_f32_e32 v81, s11, v236
	v_add_f32_e32 v52, v52, v53
	v_fma_f32 v66, s11, v236, v66
	v_fma_f32 v80, s11, v236, v80
	v_mul_f32_e32 v53, v81, v81
	v_mul_f32_e32 v54, v67, v67
	v_fmac_f32_e32 v53, v80, v80
	v_fmac_f32_e32 v54, v66, v66
	v_add_f32_e32 v53, v53, v54
	v_fmac_f32_e32 v73, s11, v236
	v_fmac_f32_e32 v69, s11, v236
	v_add_f32_e32 v52, v52, v53
	v_fma_f32 v72, s11, v236, v72
	v_fma_f32 v68, s11, v236, v68
	v_mul_f32_e32 v53, v69, v69
	v_mul_f32_e32 v54, v73, v73
	v_fmac_f32_e32 v53, v68, v68
	v_fmac_f32_e32 v54, v72, v72
	v_add_f32_e32 v53, v53, v54
	v_fmac_f32_e32 v75, s11, v236
	v_fmac_f32_e32 v71, s11, v236
	v_add_f32_e32 v52, v53, v52
	v_fma_f32 v74, s11, v236, v74
	v_fma_f32 v70, s11, v236, v70
	v_mul_f32_e32 v53, v71, v71
	v_mul_f32_e32 v54, v75, v75
	v_fmac_f32_e32 v53, v70, v70
	v_fmac_f32_e32 v54, v74, v74
	v_add_f32_e32 v53, v53, v54
	v_add_f32_e32 v52, v53, v52
	v_mov_b32_e32 v53, v2
	s_nop 0
; __device__ __forceinline__ float bflo(unsigned w) { return __uint_as_float(w << 16); }
; __device__ __forceinline__ float bfhi(unsigned w) { return __uint_as_float(w & 0xffff0000u); }
; __device__ __forceinline__ float wave_sum(float v) { return rdlane(dpp_sum63(v), 63); }
; __device__ __forceinline__ void row_ln(f32x4 (&v)[4], const float* g, const float* b, int lane) {
;     ...
;     const float rstd = 1.0f / sqrtf(wave_sum(s2) * (1.f / D) + LN_EPS);
; #pragma unroll
;     for (int j = 0; j < 4; ++j) { const f32x4 gg = *(const f32x4*)(g + RCOL(lane, j)), bb = *(const f32x4*)(b + RCOL(lane, j)); v[j] = v[j] * rstd * gg + bb; }
; __device__ __forceinline__ void ln2_phase(CArgs& A, Frame& F, int L) {
;     ...
;             u32x4 cur[2][3][2];
; #pragma unroll
;             for (int r = 0; r < 2; ++r)
; #pragma unroll
;                 for (int k = 0; k < 3; ++k) { cur[r][k][0] = nx[r][k][0]; cur[r][k][1] = nx[r][k][1]; }
;             if (m + 2 < c1) LN2_LOAD(m + 2);
; #pragma unroll
;             for (int r = 0; r < 2; ++r) { const int mm = (m + r < c1) ? m + r : c1 - 1; const int i_ = 2 * (mm - c0);
;                 const float g0 = __builtin_bit_cast(float, __builtin_amdgcn_readlane(__builtin_bit_cast(int, gtv), i_)), g1 = __builtin_bit_cast(float, __builtin_amdgcn_readlane(__builtin_bit_cast(int, gtv), i_ + 1));
;                 f32x4 v[4]; row_unpack(cur[r][0], v);
; #pragma unroll
;                 for (int j2 = 0; j2 < 2; ++j2) { const unsigned a0[4] = {cur[r][1][j2].x, cur[r][1][j2].y, cur[r][1][j2].z, cur[r][1][j2].w}, a1[4] = {cur[r][2][j2].x, cur[r][2][j2].y, cur[r][2][j2].z, cur[r][2][j2].w};
; #pragma unroll
;                     for (int q = 0; q < 4; ++q) { f32x4& vv = v[2 * j2 + (q >> 1)]; const int i0 = 2 * (q & 1);
;                         vv[i0] = vv[i0] * DN_ALPHA + (g0 * bflo(a0[q]) + g1 * bflo(a1[q])); vv[i0 + 1] = vv[i0 + 1] * DN_ALPHA + (g0 * bfhi(a0[q]) + g1 * bfhi(a1[q])); } }
;                 row_ln(v, g, bb, F.lane);
;                 row_store_bf(X + (size_t)mm * D, F.lane, v); }
	v_add_f32_dpp v52, v52, v52 quad_perm:[1,0,3,2] row_mask:0xf bank_mask:0xf bound_ctrl:1
	s_nop 1
	v_add_f32_dpp v52, v52, v52 quad_perm:[2,3,0,1] row_mask:0xf bank_mask:0xf bound_ctrl:1
	s_nop 1
	v_add_f32_dpp v52, v52, v52 row_half_mirror row_mask:0xf bank_mask:0xf bound_ctrl:1
	s_nop 1
	v_add_f32_dpp v52, v52, v52 row_mirror row_mask:0xf bank_mask:0xf bound_ctrl:1
	s_nop 1
	v_mov_b32_dpp v53, v52 row_bcast:15 row_mask:0xa bank_mask:0xf
	v_add_f32_e32 v52, v52, v53
	v_mov_b32_e32 v53, v2
	s_nop 1
	v_mov_b32_dpp v53, v52 row_bcast:31 row_mask:0xc bank_mask:0xf
	v_add_f32_e32 v52, v52, v53
	s_nop 0
	v_readlane_b32 s11, v52, 63
	s_nop 1
	v_fma_f32 v52, s11, v237, v252
	v_cmp_gt_f32_e32 vcc, s31, v52
	v_mul_f32_e32 v53, 0x4f800000, v52
	s_ashr_i32 s11, s10, 31
	v_cndmask_b32_e32 v52, v52, v53, vcc
	v_sqrt_f32_e32 v53, v52
	s_lshl_b64 s[10:11], s[10:11], 11
	s_cmp_ge_i32 s18, s16
	v_add_u32_e32 v54, -1, v53
	v_fma_f32 v55, -v54, v53, v52
	v_cmp_ge_f32_e64 s[38:39], 0, v55
	v_add_u32_e32 v55, 1, v53
	s_nop 0
	v_cndmask_b32_e64 v54, v53, v54, s[38:39]
	v_fma_f32 v53, -v55, v53, v52
	v_cmp_lt_f32_e64 s[38:39], 0, v53
	s_nop 1
	v_cndmask_b32_e64 v53, v54, v55, s[38:39]
	v_mul_f32_e32 v54, 0x37800000, v53
	v_cndmask_b32_e32 v53, v53, v54, vcc
	v_cmp_class_f32_e32 vcc, v52, v234
	s_nop 1
	v_cndmask_b32_e32 v52, v53, v52, vcc
	v_div_scale_f32 v53, s[12:13], v52, v52, 1.0
	v_rcp_f32_e32 v54, v53
	s_nop 0
	v_fma_f32 v55, -v53, v54, 1.0
	v_fmac_f32_e32 v54, v55, v54
	v_div_scale_f32 v55, vcc, 1.0, v52, 1.0
	v_mul_f32_e32 v56, v55, v54
	v_fma_f32 v57, -v53, v56, v55
	v_fmac_f32_e32 v56, v57, v54
	v_fma_f32 v53, -v53, v56, v55
	v_div_fmas_f32 v53, v53, v54, v56
	v_div_fixup_f32 v76, v53, v52, 1.0
	v_mov_b64_e32 v[52:53], v[128:129]
	v_mov_b64_e32 v[54:55], v[130:131]
	v_mov_b64_e32 v[56:57], v[124:125]
	v_mov_b64_e32 v[58:59], v[126:127]
	v_mov_b64_e32 v[60:61], v[144:145]
	v_mov_b64_e32 v[62:63], v[146:147]
	v_mov_b64_e32 v[82:83], v[140:141]
	v_mov_b64_e32 v[84:85], v[142:143]
	v_pk_mul_f32 v[86:87], v[78:79], v[76:77] op_sel_hi:[1,0]
	v_pk_mul_f32 v[64:65], v[64:65], v[76:77] op_sel_hi:[1,0]
	v_pk_mul_f32 v[68:69], v[68:69], v[76:77] op_sel_hi:[1,0]
	v_pk_mul_f32 v[72:73], v[72:73], v[76:77] op_sel_hi:[1,0]
	v_pk_fma_f32 v[78:79], v[58:59], v[64:65], v[84:85]
	v_pk_fma_f32 v[82:83], v[56:57], v[86:87], v[82:83]
	v_pk_mul_f32 v[56:57], v[80:81], v[76:77] op_sel_hi:[1,0]
	v_pk_mul_f32 v[58:59], v[66:67], v[76:77] op_sel_hi:[1,0]
	v_pk_fma_f32 v[84:85], v[52:53], v[56:57], v[60:61]
	v_pk_fma_f32 v[80:81], v[54:55], v[58:59], v[62:63]
	v_mov_b64_e32 v[52:53], v[136:137]
	v_mov_b64_e32 v[54:55], v[138:139]
	v_mov_b64_e32 v[60:61], v[132:133]
	v_mov_b64_e32 v[62:63], v[134:135]
	v_mov_b64_e32 v[56:57], v[152:153]
	v_mov_b64_e32 v[58:59], v[154:155]
	v_mov_b64_e32 v[64:65], v[148:149]
	v_mov_b64_e32 v[66:67], v[150:151]
	v_pk_fma_f32 v[62:63], v[62:63], v[72:73], v[66:67]
	v_pk_fma_f32 v[60:61], v[60:61], v[68:69], v[64:65]
	v_pk_mul_f32 v[64:65], v[70:71], v[76:77] op_sel_hi:[1,0]
	v_pk_mul_f32 v[66:67], v[74:75], v[76:77] op_sel_hi:[1,0]
	v_pk_fma_f32 v[56:57], v[52:53], v[64:65], v[56:57]
	v_pk_fma_f32 v[58:59], v[54:55], v[66:67], v[58:59]
	v_lshl_add_u64 v[64:65], v[100:101], 0, s[10:11]
	v_cvt_pk_bf16_f32 v52, v82, v83
	v_cvt_pk_bf16_f32 v53, v78, v79
	v_cvt_pk_bf16_f32 v54, v84, v85
	v_cvt_pk_bf16_f32 v55, v80, v81
	global_store_dwordx4 v[64:65], v[52:55], off
	s_mov_b64 s[10:11], 0x1000
	s_nop 0
	v_cvt_pk_bf16_f32 v52, v60, v61
	v_cvt_pk_bf16_f32 v53, v62, v63
	v_cvt_pk_bf16_f32 v54, v56, v57
	v_cvt_pk_bf16_f32 v55, v58, v59
	global_store_dwordx4 v[64:65], v[52:55], off offset:1024
	s_waitcnt vmcnt(4)
	v_mov_b64_e32 v[98:99], v[6:7]
	v_mov_b64_e32 v[94:95], v[14:15]
	v_mov_b64_e32 v[90:91], v[22:23]
	v_mov_b64_e32 v[96:97], v[4:5]
	v_mov_b64_e32 v[92:93], v[12:13]
	v_mov_b64_e32 v[88:89], v[20:21]
	v_mov_b64_e32 v[86:87], v[10:11]
	v_mov_b64_e32 v[82:83], v[18:19]
	v_mov_b64_e32 v[78:79], v[26:27]
	v_mov_b64_e32 v[74:75], v[30:31]
	v_mov_b64_e32 v[62:63], v[34:35]
	v_mov_b64_e32 v[70:71], v[38:39]
	v_mov_b64_e32 v[58:59], v[42:43]
	v_mov_b64_e32 v[66:67], v[46:47]
	v_mov_b64_e32 v[54:55], v[50:51]
	v_lshl_add_u64 v[106:107], v[106:107], 0, s[10:11]
	v_mov_b64_e32 v[84:85], v[8:9]
	v_mov_b64_e32 v[80:81], v[16:17]
	v_mov_b64_e32 v[76:77], v[24:25]
	v_mov_b64_e32 v[72:73], v[28:29]
	v_mov_b64_e32 v[60:61], v[32:33]
	v_mov_b64_e32 v[68:69], v[36:37]
	v_mov_b64_e32 v[56:57], v[40:41]
	v_mov_b64_e32 v[64:65], v[44:45]
	v_mov_b64_e32 v[52:53], v[48:49]
	s_cbranch_scc1 .LBB0_1486
